# prompt-attention unit output (ocat bf16) stored 16 bytes per lane via permlane32_swap pairing (4 stores instead of 8)
# speedup vs baseline: 1.0209x; 1.0015x over previous
.LBB0_1276:
	v_lshlrev_b64 v[4:5], 12, v[162:163]
	v_lshl_add_u64 v[4:5], s[58:59], 0, v[4:5]
	v_lshlrev_b32_e32 v6, 1, v155
	v_mov_b32_e32 v7, v2
	v_lshl_add_u64 v[8:9], v[4:5], 0, v[6:7]
	v_mov_b32_e32 v161, v2
	v_lshl_add_u64 v[16:17], v[8:9], 0, v[160:161]
	v_mbcnt_lo_u32_b32 v36, -1, 0
	v_mbcnt_hi_u32_b32 v36, -1, v36
	ds_read_b128 v[40:43], v193
	ds_read_b128 v[44:47], v193 offset:32
	ds_read_b128 v[48:51], v193 offset:64
	ds_read_b128 v[52:55], v193 offset:96
	ds_read_b128 v[56:59], v193 offset:128
	ds_read_b128 v[60:63], v193 offset:160
	ds_read_b128 v[64:67], v193 offset:192
	ds_read_b128 v[68:71], v193 offset:224
	v_lshrrev_b32_e32 v36, 5, v36
	v_mov_b32_e32 v37, v2
	v_lshlrev_b32_e32 v36, 3, v36
	v_readlane_b32 s0, v253, 42
	v_lshl_add_u64 v[16:17], v[36:37], 0, v[16:17]
	s_waitcnt lgkmcnt(0)
	v_cvt_pk_bf16_f32 v72, v40, v41
	v_cvt_pk_bf16_f32 v73, v42, v43
	v_cvt_pk_bf16_f32 v74, v44, v45
	v_cvt_pk_bf16_f32 v75, v46, v47
	v_cvt_pk_bf16_f32 v76, v48, v49
	v_cvt_pk_bf16_f32 v77, v50, v51
	v_cvt_pk_bf16_f32 v78, v52, v53
	v_cvt_pk_bf16_f32 v79, v54, v55
	v_cvt_pk_bf16_f32 v80, v56, v57
	v_cvt_pk_bf16_f32 v81, v58, v59
	v_cvt_pk_bf16_f32 v82, v60, v61
	v_cvt_pk_bf16_f32 v83, v62, v63
	v_cvt_pk_bf16_f32 v84, v64, v65
	v_cvt_pk_bf16_f32 v85, v66, v67
	v_cvt_pk_bf16_f32 v86, v68, v69
	v_cvt_pk_bf16_f32 v87, v70, v71
	s_nop 1
	v_permlane32_swap_b32_e32 v72, v74
	v_permlane32_swap_b32_e32 v73, v75
	v_permlane32_swap_b32_e32 v76, v78
	v_permlane32_swap_b32_e32 v77, v79
	v_permlane32_swap_b32_e32 v80, v82
	v_permlane32_swap_b32_e32 v81, v83
	v_permlane32_swap_b32_e32 v84, v86
	v_permlane32_swap_b32_e32 v85, v87
	global_store_dwordx4 v[16:17], v[72:75], off
	global_store_dwordx4 v[16:17], v[76:79], off offset:32
	global_store_dwordx4 v[16:17], v[80:83], off offset:64
	global_store_dwordx4 v[16:17], v[84:87], off offset:96
	s_add_i32 s33, s33, s0
	s_cmpk_gt_i32 s33, 0x3ff
	s_cbranch_scc1 .LBB0_1468
